# cv32 + code placement: the five GEMM K-loop heads aligned to 64 bytes (.p2align 6)
# speedup vs baseline: 1.0057x; 1.0057x over previous
.LBB0_305:
	s_ashr_i32 s47, s46, 31
	s_lshl_b64 s[16:17], s[46:47], 20
	s_add_u32 s48, s6, s16
	s_addc_u32 s49, s20, s17
	s_and_b64 s[16:17], s[40:41], exec
	s_cselect_b32 s9, s49, s37
	s_cselect_b32 s14, s48, s36
	s_ashr_i32 s45, s44, 31
	s_lshl_b64 s[16:17], s[44:45], 20
	s_add_u32 s50, s31, s16
	s_addc_u32 s51, s52, s17
	s_and_b64 s[16:17], s[40:41], exec
	s_cselect_b32 s16, s51, s39
	s_cselect_b32 s17, s50, s38
	s_add_u32 s36, s36, 0x80080
	s_addc_u32 s37, s37, 0
	s_add_u32 s25, s38, 0x100
	v_mov_b32_e32 v2, 0
	s_addc_u32 s26, s39, 0
	s_mov_b32 s27, -2
	v_mov_b32_e32 v3, v2
	v_mov_b32_e32 v4, v2
	v_mov_b32_e32 v5, v2
	v_mov_b32_e32 v6, v2
	v_mov_b32_e32 v7, v2
	v_mov_b32_e32 v8, v2
	v_mov_b32_e32 v9, v2
	v_mov_b32_e32 v22, v2
	v_mov_b32_e32 v23, v2
	v_mov_b32_e32 v24, v2
	v_mov_b32_e32 v25, v2
	v_mov_b32_e32 v26, v2
	v_mov_b32_e32 v27, v2
	v_mov_b32_e32 v28, v2
	v_mov_b32_e32 v29, v2
	v_mov_b32_e32 v40, v2
	v_mov_b32_e32 v41, v2
	v_mov_b32_e32 v42, v2
	v_mov_b32_e32 v43, v2
	v_mov_b32_e32 v44, v2
	v_mov_b32_e32 v45, v2
	v_mov_b32_e32 v46, v2
	v_mov_b32_e32 v47, v2
	v_mov_b32_e32 v56, v2
	v_mov_b32_e32 v57, v2
	v_mov_b32_e32 v58, v2
	v_mov_b32_e32 v59, v2
	v_mov_b32_e32 v60, v2
	v_mov_b32_e32 v61, v2
	v_mov_b32_e32 v62, v2
	v_mov_b32_e32 v63, v2
	v_mov_b32_e32 v10, v2
	v_mov_b32_e32 v11, v2
	v_mov_b32_e32 v12, v2
	v_mov_b32_e32 v13, v2
	v_mov_b32_e32 v18, v2
	v_mov_b32_e32 v19, v2
	v_mov_b32_e32 v20, v2
	v_mov_b32_e32 v21, v2
	v_mov_b32_e32 v30, v2
	v_mov_b32_e32 v31, v2
	v_mov_b32_e32 v32, v2
	v_mov_b32_e32 v33, v2
	v_mov_b32_e32 v36, v2
	v_mov_b32_e32 v37, v2
	v_mov_b32_e32 v38, v2
	v_mov_b32_e32 v39, v2
	v_mov_b32_e32 v48, v2
	v_mov_b32_e32 v49, v2
	v_mov_b32_e32 v50, v2
	v_mov_b32_e32 v51, v2
	v_mov_b32_e32 v52, v2
	v_mov_b32_e32 v53, v2
	v_mov_b32_e32 v54, v2
	v_mov_b32_e32 v55, v2
	v_mov_b32_e32 v64, v2
	v_mov_b32_e32 v65, v2
	v_mov_b32_e32 v66, v2
	v_mov_b32_e32 v67, v2
	v_mov_b32_e32 v68, v2
	v_mov_b32_e32 v69, v2
	v_mov_b32_e32 v70, v2
	v_mov_b32_e32 v71, v2
	v_mov_b32_e32 v72, v2
	v_mov_b32_e32 v73, v2
	v_mov_b32_e32 v74, v2
	v_mov_b32_e32 v75, v2
	v_mov_b32_e32 v76, v2
	v_mov_b32_e32 v77, v2
	v_mov_b32_e32 v78, v2
	v_mov_b32_e32 v79, v2
	v_mov_b32_e32 v88, v2
	v_mov_b32_e32 v89, v2
	v_mov_b32_e32 v90, v2
	v_mov_b32_e32 v91, v2
	v_mov_b32_e32 v92, v2
	v_mov_b32_e32 v93, v2
	v_mov_b32_e32 v94, v2
	v_mov_b32_e32 v95, v2
	v_mov_b32_e32 v104, v2
	v_mov_b32_e32 v105, v2
	v_mov_b32_e32 v106, v2
	v_mov_b32_e32 v107, v2
	v_mov_b32_e32 v108, v2
	v_mov_b32_e32 v109, v2
	v_mov_b32_e32 v110, v2
	v_mov_b32_e32 v111, v2
	v_mov_b32_e32 v120, v2
	v_mov_b32_e32 v121, v2
	v_mov_b32_e32 v122, v2
	v_mov_b32_e32 v123, v2
	v_mov_b32_e32 v124, v2
	v_mov_b32_e32 v125, v2
	v_mov_b32_e32 v126, v2
	v_mov_b32_e32 v127, v2
	v_mov_b32_e32 v80, v2
	v_mov_b32_e32 v81, v2
	v_mov_b32_e32 v82, v2
	v_mov_b32_e32 v83, v2
	v_mov_b32_e32 v84, v2
	v_mov_b32_e32 v85, v2
	v_mov_b32_e32 v86, v2
	v_mov_b32_e32 v87, v2
	v_mov_b32_e32 v96, v2
	v_mov_b32_e32 v97, v2
	v_mov_b32_e32 v98, v2
	v_mov_b32_e32 v99, v2
	v_mov_b32_e32 v100, v2
	v_mov_b32_e32 v101, v2
	v_mov_b32_e32 v102, v2
	v_mov_b32_e32 v103, v2
	v_mov_b32_e32 v112, v2
	v_mov_b32_e32 v113, v2
	v_mov_b32_e32 v114, v2
	v_mov_b32_e32 v115, v2
	v_mov_b32_e32 v116, v2
	v_mov_b32_e32 v117, v2
	v_mov_b32_e32 v118, v2
	v_mov_b32_e32 v119, v2
	v_mov_b32_e32 v128, v2
	v_mov_b32_e32 v129, v2
	v_mov_b32_e32 v130, v2
	v_mov_b32_e32 v131, v2
	v_mov_b32_e32 v132, v2
	v_mov_b32_e32 v133, v2
	v_mov_b32_e32 v134, v2
	v_mov_b32_e32 v135, v2
	.p2align 6

.LBB0_1123:
	s_add_i32 s29, s51, -2
	s_add_u32 s70, s38, 0x100
	s_addc_u32 s71, s39, 0
	s_mov_b32 s44, 0
	.p2align 6

.LBB0_1507:
	s_add_i32 s9, s71, -2
	s_add_u32 s48, s48, 0x80080
	s_addc_u32 s49, s49, 0
	s_add_u32 s13, s50, 0x100
	v_mov_b32_e32 v2, 0
	s_addc_u32 s29, s51, 0
	s_mov_b32 s35, 0
	v_mov_b32_e32 v3, v2
	v_mov_b32_e32 v4, v2
	v_mov_b32_e32 v5, v2
	v_mov_b32_e32 v6, v2
	v_mov_b32_e32 v7, v2
	v_mov_b32_e32 v8, v2
	v_mov_b32_e32 v9, v2
	v_mov_b32_e32 v22, v2
	v_mov_b32_e32 v23, v2
	v_mov_b32_e32 v24, v2
	v_mov_b32_e32 v25, v2
	v_mov_b32_e32 v26, v2
	v_mov_b32_e32 v27, v2
	v_mov_b32_e32 v28, v2
	v_mov_b32_e32 v29, v2
	v_mov_b32_e32 v40, v2
	v_mov_b32_e32 v41, v2
	v_mov_b32_e32 v42, v2
	v_mov_b32_e32 v43, v2
	v_mov_b32_e32 v44, v2
	v_mov_b32_e32 v45, v2
	v_mov_b32_e32 v46, v2
	v_mov_b32_e32 v47, v2
	v_mov_b32_e32 v56, v2
	v_mov_b32_e32 v57, v2
	v_mov_b32_e32 v58, v2
	v_mov_b32_e32 v59, v2
	v_mov_b32_e32 v60, v2
	v_mov_b32_e32 v61, v2
	v_mov_b32_e32 v62, v2
	v_mov_b32_e32 v63, v2
	v_mov_b32_e32 v10, v2
	v_mov_b32_e32 v11, v2
	v_mov_b32_e32 v12, v2
	v_mov_b32_e32 v13, v2
	v_mov_b32_e32 v18, v2
	v_mov_b32_e32 v19, v2
	v_mov_b32_e32 v20, v2
	v_mov_b32_e32 v21, v2
	v_mov_b32_e32 v30, v2
	v_mov_b32_e32 v31, v2
	v_mov_b32_e32 v32, v2
	v_mov_b32_e32 v33, v2
	v_mov_b32_e32 v36, v2
	v_mov_b32_e32 v37, v2
	v_mov_b32_e32 v38, v2
	v_mov_b32_e32 v39, v2
	v_mov_b32_e32 v48, v2
	v_mov_b32_e32 v49, v2
	v_mov_b32_e32 v50, v2
	v_mov_b32_e32 v51, v2
	v_mov_b32_e32 v52, v2
	v_mov_b32_e32 v53, v2
	v_mov_b32_e32 v54, v2
	v_mov_b32_e32 v55, v2
	v_mov_b32_e32 v64, v2
	v_mov_b32_e32 v65, v2
	v_mov_b32_e32 v66, v2
	v_mov_b32_e32 v67, v2
	v_mov_b32_e32 v68, v2
	v_mov_b32_e32 v69, v2
	v_mov_b32_e32 v70, v2
	v_mov_b32_e32 v71, v2
	v_mov_b32_e32 v72, v2
	v_mov_b32_e32 v73, v2
	v_mov_b32_e32 v74, v2
	v_mov_b32_e32 v75, v2
	v_mov_b32_e32 v76, v2
	v_mov_b32_e32 v77, v2
	v_mov_b32_e32 v78, v2
	v_mov_b32_e32 v79, v2
	v_mov_b32_e32 v88, v2
	v_mov_b32_e32 v89, v2
	v_mov_b32_e32 v90, v2
	v_mov_b32_e32 v91, v2
	v_mov_b32_e32 v92, v2
	v_mov_b32_e32 v93, v2
	v_mov_b32_e32 v94, v2
	v_mov_b32_e32 v95, v2
	v_mov_b32_e32 v104, v2
	v_mov_b32_e32 v105, v2
	v_mov_b32_e32 v106, v2
	v_mov_b32_e32 v107, v2
	v_mov_b32_e32 v108, v2
	v_mov_b32_e32 v109, v2
	v_mov_b32_e32 v110, v2
	v_mov_b32_e32 v111, v2
	v_mov_b32_e32 v120, v2
	v_mov_b32_e32 v121, v2
	v_mov_b32_e32 v122, v2
	v_mov_b32_e32 v123, v2
	v_mov_b32_e32 v124, v2
	v_mov_b32_e32 v125, v2
	v_mov_b32_e32 v126, v2
	v_mov_b32_e32 v127, v2
	v_mov_b32_e32 v80, v2
	v_mov_b32_e32 v81, v2
	v_mov_b32_e32 v82, v2
	v_mov_b32_e32 v83, v2
	v_mov_b32_e32 v84, v2
	v_mov_b32_e32 v85, v2
	v_mov_b32_e32 v86, v2
	v_mov_b32_e32 v87, v2
	v_mov_b32_e32 v96, v2
	v_mov_b32_e32 v97, v2
	v_mov_b32_e32 v98, v2
	v_mov_b32_e32 v99, v2
	v_mov_b32_e32 v100, v2
	v_mov_b32_e32 v101, v2
	v_mov_b32_e32 v102, v2
	v_mov_b32_e32 v103, v2
	v_mov_b32_e32 v112, v2
	v_mov_b32_e32 v113, v2
	v_mov_b32_e32 v114, v2
	v_mov_b32_e32 v115, v2
	v_mov_b32_e32 v116, v2
	v_mov_b32_e32 v117, v2
	v_mov_b32_e32 v118, v2
	v_mov_b32_e32 v119, v2
	v_mov_b32_e32 v128, v2
	v_mov_b32_e32 v129, v2
	v_mov_b32_e32 v130, v2
	v_mov_b32_e32 v131, v2
	v_mov_b32_e32 v132, v2
	v_mov_b32_e32 v133, v2
	v_mov_b32_e32 v134, v2
	v_mov_b32_e32 v135, v2
	.p2align 6

.LBB0_1663:
	s_ashr_i32 s29, s28, 31
	s_lshl_b64 s[34:35], s[28:29], 20
	s_add_u32 s34, s6, s34
	s_addc_u32 s35, s14, s35
	s_and_b64 s[36:37], s[38:39], exec
	s_cselect_b32 s29, s35, s43
	s_cselect_b32 s53, s34, s42
	s_ashr_i32 s13, s12, 31
	s_lshl_b64 s[36:37], s[12:13], 20
	s_add_u32 s36, s16, s36
	s_addc_u32 s37, s17, s37
	s_and_b64 s[46:47], s[38:39], exec
	s_cselect_b32 s13, s37, s45
	s_cselect_b32 s54, s36, s44
	s_add_u32 s42, s42, 0x80080
	s_addc_u32 s43, s43, 0
	s_add_u32 s55, s44, 0x100
	v_mov_b32_e32 v2, 0
	s_addc_u32 s60, s45, 0
	s_mov_b32 s61, -2
	v_mov_b32_e32 v3, v2
	v_mov_b32_e32 v4, v2
	v_mov_b32_e32 v5, v2
	v_mov_b32_e32 v6, v2
	v_mov_b32_e32 v7, v2
	v_mov_b32_e32 v8, v2
	v_mov_b32_e32 v9, v2
	v_mov_b32_e32 v22, v2
	v_mov_b32_e32 v23, v2
	v_mov_b32_e32 v24, v2
	v_mov_b32_e32 v25, v2
	v_mov_b32_e32 v26, v2
	v_mov_b32_e32 v27, v2
	v_mov_b32_e32 v28, v2
	v_mov_b32_e32 v29, v2
	v_mov_b32_e32 v40, v2
	v_mov_b32_e32 v41, v2
	v_mov_b32_e32 v42, v2
	v_mov_b32_e32 v43, v2
	v_mov_b32_e32 v44, v2
	v_mov_b32_e32 v45, v2
	v_mov_b32_e32 v46, v2
	v_mov_b32_e32 v47, v2
	v_mov_b32_e32 v56, v2
	v_mov_b32_e32 v57, v2
	v_mov_b32_e32 v58, v2
	v_mov_b32_e32 v59, v2
	v_mov_b32_e32 v60, v2
	v_mov_b32_e32 v61, v2
	v_mov_b32_e32 v62, v2
	v_mov_b32_e32 v63, v2
	v_mov_b32_e32 v10, v2
	v_mov_b32_e32 v11, v2
	v_mov_b32_e32 v12, v2
	v_mov_b32_e32 v13, v2
	v_mov_b32_e32 v18, v2
	v_mov_b32_e32 v19, v2
	v_mov_b32_e32 v20, v2
	v_mov_b32_e32 v21, v2
	v_mov_b32_e32 v30, v2
	v_mov_b32_e32 v31, v2
	v_mov_b32_e32 v32, v2
	v_mov_b32_e32 v33, v2
	v_mov_b32_e32 v36, v2
	v_mov_b32_e32 v37, v2
	v_mov_b32_e32 v38, v2
	v_mov_b32_e32 v39, v2
	v_mov_b32_e32 v48, v2
	v_mov_b32_e32 v49, v2
	v_mov_b32_e32 v50, v2
	v_mov_b32_e32 v51, v2
	v_mov_b32_e32 v52, v2
	v_mov_b32_e32 v53, v2
	v_mov_b32_e32 v54, v2
	v_mov_b32_e32 v55, v2
	v_mov_b32_e32 v64, v2
	v_mov_b32_e32 v65, v2
	v_mov_b32_e32 v66, v2
	v_mov_b32_e32 v67, v2
	v_mov_b32_e32 v68, v2
	v_mov_b32_e32 v69, v2
	v_mov_b32_e32 v70, v2
	v_mov_b32_e32 v71, v2
	v_mov_b32_e32 v72, v2
	v_mov_b32_e32 v73, v2
	v_mov_b32_e32 v74, v2
	v_mov_b32_e32 v75, v2
	v_mov_b32_e32 v76, v2
	v_mov_b32_e32 v77, v2
	v_mov_b32_e32 v78, v2
	v_mov_b32_e32 v79, v2
	v_mov_b32_e32 v88, v2
	v_mov_b32_e32 v89, v2
	v_mov_b32_e32 v90, v2
	v_mov_b32_e32 v91, v2
	v_mov_b32_e32 v92, v2
	v_mov_b32_e32 v93, v2
	v_mov_b32_e32 v94, v2
	v_mov_b32_e32 v95, v2
	v_mov_b32_e32 v104, v2
	v_mov_b32_e32 v105, v2
	v_mov_b32_e32 v106, v2
	v_mov_b32_e32 v107, v2
	v_mov_b32_e32 v108, v2
	v_mov_b32_e32 v109, v2
	v_mov_b32_e32 v110, v2
	v_mov_b32_e32 v111, v2
	v_mov_b32_e32 v120, v2
	v_mov_b32_e32 v121, v2
	v_mov_b32_e32 v122, v2
	v_mov_b32_e32 v123, v2
	v_mov_b32_e32 v124, v2
	v_mov_b32_e32 v125, v2
	v_mov_b32_e32 v126, v2
	v_mov_b32_e32 v127, v2
	v_mov_b32_e32 v80, v2
	v_mov_b32_e32 v81, v2
	v_mov_b32_e32 v82, v2
	v_mov_b32_e32 v83, v2
	v_mov_b32_e32 v84, v2
	v_mov_b32_e32 v85, v2
	v_mov_b32_e32 v86, v2
	v_mov_b32_e32 v87, v2
	v_mov_b32_e32 v96, v2
	v_mov_b32_e32 v97, v2
	v_mov_b32_e32 v98, v2
	v_mov_b32_e32 v99, v2
	v_mov_b32_e32 v100, v2
	v_mov_b32_e32 v101, v2
	v_mov_b32_e32 v102, v2
	v_mov_b32_e32 v103, v2
	v_mov_b32_e32 v112, v2
	v_mov_b32_e32 v113, v2
	v_mov_b32_e32 v114, v2
	v_mov_b32_e32 v115, v2
	v_mov_b32_e32 v116, v2
	v_mov_b32_e32 v117, v2
	v_mov_b32_e32 v118, v2
	v_mov_b32_e32 v119, v2
	v_mov_b32_e32 v128, v2
	v_mov_b32_e32 v129, v2
	v_mov_b32_e32 v130, v2
	v_mov_b32_e32 v131, v2
	v_mov_b32_e32 v132, v2
	v_mov_b32_e32 v133, v2
	v_mov_b32_e32 v134, v2
	v_mov_b32_e32 v135, v2
	.p2align 6

.LBB0_1763:
	s_add_i32 s11, s67, -2
	s_add_u32 s70, s42, 0x100
	v_mov_b32_e32 v2, 0
	s_addc_u32 s71, s43, 0
	s_mov_b32 s44, 0
	v_mov_b32_e32 v3, v2
	v_mov_b32_e32 v4, v2
	v_mov_b32_e32 v5, v2
	v_mov_b32_e32 v6, v2
	v_mov_b32_e32 v7, v2
	v_mov_b32_e32 v8, v2
	v_mov_b32_e32 v9, v2
	v_mov_b32_e32 v22, v2
	v_mov_b32_e32 v23, v2
	v_mov_b32_e32 v24, v2
	v_mov_b32_e32 v25, v2
	v_mov_b32_e32 v26, v2
	v_mov_b32_e32 v27, v2
	v_mov_b32_e32 v28, v2
	v_mov_b32_e32 v29, v2
	v_mov_b32_e32 v40, v2
	v_mov_b32_e32 v41, v2
	v_mov_b32_e32 v42, v2
	v_mov_b32_e32 v43, v2
	v_mov_b32_e32 v44, v2
	v_mov_b32_e32 v45, v2
	v_mov_b32_e32 v46, v2
	v_mov_b32_e32 v47, v2
	v_mov_b32_e32 v56, v2
	v_mov_b32_e32 v57, v2
	v_mov_b32_e32 v58, v2
	v_mov_b32_e32 v59, v2
	v_mov_b32_e32 v60, v2
	v_mov_b32_e32 v61, v2
	v_mov_b32_e32 v62, v2
	v_mov_b32_e32 v63, v2
	v_mov_b32_e32 v10, v2
	v_mov_b32_e32 v11, v2
	v_mov_b32_e32 v12, v2
	v_mov_b32_e32 v13, v2
	v_mov_b32_e32 v18, v2
	v_mov_b32_e32 v19, v2
	v_mov_b32_e32 v20, v2
	v_mov_b32_e32 v21, v2
	v_mov_b32_e32 v30, v2
	v_mov_b32_e32 v31, v2
	v_mov_b32_e32 v32, v2
	v_mov_b32_e32 v33, v2
	v_mov_b32_e32 v36, v2
	v_mov_b32_e32 v37, v2
	v_mov_b32_e32 v38, v2
	v_mov_b32_e32 v39, v2
	v_mov_b32_e32 v48, v2
	v_mov_b32_e32 v49, v2
	v_mov_b32_e32 v50, v2
	v_mov_b32_e32 v51, v2
	v_mov_b32_e32 v52, v2
	v_mov_b32_e32 v53, v2
	v_mov_b32_e32 v54, v2
	v_mov_b32_e32 v55, v2
	v_mov_b32_e32 v64, v2
	v_mov_b32_e32 v65, v2
	v_mov_b32_e32 v66, v2
	v_mov_b32_e32 v67, v2
	v_mov_b32_e32 v68, v2
	v_mov_b32_e32 v69, v2
	v_mov_b32_e32 v70, v2
	v_mov_b32_e32 v71, v2
	v_mov_b32_e32 v72, v2
	v_mov_b32_e32 v73, v2
	v_mov_b32_e32 v74, v2
	v_mov_b32_e32 v75, v2
	v_mov_b32_e32 v76, v2
	v_mov_b32_e32 v77, v2
	v_mov_b32_e32 v78, v2
	v_mov_b32_e32 v79, v2
	v_mov_b32_e32 v88, v2
	v_mov_b32_e32 v89, v2
	v_mov_b32_e32 v90, v2
	v_mov_b32_e32 v91, v2
	v_mov_b32_e32 v92, v2
	v_mov_b32_e32 v93, v2
	v_mov_b32_e32 v94, v2
	v_mov_b32_e32 v95, v2
	v_mov_b32_e32 v104, v2
	v_mov_b32_e32 v105, v2
	v_mov_b32_e32 v106, v2
	v_mov_b32_e32 v107, v2
	v_mov_b32_e32 v108, v2
	v_mov_b32_e32 v109, v2
	v_mov_b32_e32 v110, v2
	v_mov_b32_e32 v111, v2
	v_mov_b32_e32 v120, v2
	v_mov_b32_e32 v121, v2
	v_mov_b32_e32 v122, v2
	v_mov_b32_e32 v123, v2
	v_mov_b32_e32 v124, v2
	v_mov_b32_e32 v125, v2
	v_mov_b32_e32 v126, v2
	v_mov_b32_e32 v127, v2
	v_mov_b32_e32 v80, v2
	v_mov_b32_e32 v81, v2
	v_mov_b32_e32 v82, v2
	v_mov_b32_e32 v83, v2
	v_mov_b32_e32 v84, v2
	v_mov_b32_e32 v85, v2
	v_mov_b32_e32 v86, v2
	v_mov_b32_e32 v87, v2
	v_mov_b32_e32 v96, v2
	v_mov_b32_e32 v97, v2
	v_mov_b32_e32 v98, v2
	v_mov_b32_e32 v99, v2
	v_mov_b32_e32 v100, v2
	v_mov_b32_e32 v101, v2
	v_mov_b32_e32 v102, v2
	v_mov_b32_e32 v103, v2
	v_mov_b32_e32 v112, v2
	v_mov_b32_e32 v113, v2
	v_mov_b32_e32 v114, v2
	v_mov_b32_e32 v115, v2
	v_mov_b32_e32 v116, v2
	v_mov_b32_e32 v117, v2
	v_mov_b32_e32 v118, v2
	v_mov_b32_e32 v119, v2
	v_mov_b32_e32 v128, v2
	v_mov_b32_e32 v129, v2
	v_mov_b32_e32 v130, v2
	v_mov_b32_e32 v131, v2
	v_mov_b32_e32 v132, v2
	v_mov_b32_e32 v133, v2
	v_mov_b32_e32 v134, v2
	v_mov_b32_e32 v135, v2
	.p2align 6
